# GLORA phase: odd workgroups run the LoRA GEMMs before the attention group-combine (phase-order alternation, third instance)
# baseline (speedup 1.0000x reference)
; __device__ __forceinline__ int lane_now() { int l; asm volatile("v_mbcnt_lo_u32_b32 %0, -1, 0\n\tv_mbcnt_hi_u32_b32 %0, -1, %0" : "=v"(l)); return l; }
; __device__ __forceinline__ u32x4 pack8(f32x4 a, f32x4 b) { u32x4 w; w.x = pg8::cvt_pk_bf16(a[0], a[1]); w.y = pg8::cvt_pk_bf16(a[2], a[3]); w.z = pg8::cvt_pk_bf16(b[0], b[1]); w.w = pg8::cvt_pk_bf16(b[2], b[3]); return w; }
; #define PH(k, ...) do { if (ka->ph_lo <= (k) && (k) < ka->ph_hi) { MKCTX(); __VA_ARGS__; if ((k) == PROBE_DUP) { GSYNC(); __VA_ARGS__; } if ((k) + 1 < ka->ph_hi) GSYNC(); } } while (0)
; __device__ __forceinline__ void ph_attn_combine(Ctx& C) {
;     const int lane = lane_now(); const bf16* og = (const bf16*)(C.ws + WS_OG); const float* lse = (const float*)(C.ws + WS_LSE); bf16* oa = (bf16*)(C.ws + WS_OATT);
;     const int ntask = S * 64;
;     for (int task = (C.bid * NWAVES + C.wave) * 64 + lane; task < ntask; task += C.nb * NTHR) { const int t = task >> 6, c8 = task & 63, h = c8 >> 3;
;         const float l0 = lse[(size_t)t * 8 + h], l1 = lse[((size_t)S + t) * 8 + h], l2 = lse[((size_t)2 * S + t) * 8 + h]; const float mx = fmaxf(l0, fmaxf(l1, l2));
;         const float w0 = __expf(l0 - mx), w1 = __expf(l1 - mx), w2 = __expf(l2 - mx), rs = 1.0f / (w0 + w1 + w2);
;         float a0[8], a1[8], a2[8]; unpack8(*(const u32x4*)(og + (size_t)t * 512 + 8 * c8), a0); unpack8(*(const u32x4*)(og + ((size_t)S + t) * 512 + 8 * c8), a1); unpack8(*(const u32x4*)(og + ((size_t)2 * S + t) * 512 + 8 * c8), a2);
;         f32x4 o0, o1;
; #pragma unroll
;         for (int e = 0; e < 4; ++e) { o0[e] = (w0 * a0[e] + w1 * a1[e] + w2 * a2[e]) * rs; o1[e] = (w0 * a0[4 + e] + w1 * a1[4 + e] + w2 * a2[4 + e]) * rs; }
;         *(u32x4*)(oa + (size_t)t * 512 + 8 * c8) = pack8(o0, o1); }
; template <bool COOP>
; __global__ void __launch_bounds__(NTHR, 2) mega(Args args) {
;     ...
;     PH(P_GLORA, ph_attn_combine(C); __syncthreads(); ph_glora(C));
.LBB0_626:
	s_mov_b32 s100, 0
	s_load_dword s0, s[88:89], 0xd8
	s_waitcnt lgkmcnt(0)
	s_cmp_gt_i32 s0, 4
	s_cbranch_scc1 .LBB0_699
	s_load_dword s0, s[88:89], 0xdc
	s_waitcnt lgkmcnt(0)
	s_cmp_lt_i32 s0, 5
	s_cbranch_scc1 .LBB0_699
.Lgl_setup:
	v_readlane_b32 s0, v231, 1
	v_readlane_b32 s1, v231, 2
	s_load_dwordx2 s[4:5], s[88:89], 0xd0
	s_load_dword s48, s[0:1], 0xe0
	v_readlane_b32 s0, v231, 0
	s_lshl_b32 s0, s0, 9
	s_lshl_b32 s1, s92, 6
	s_add_i32 s1, s1, s0
	v_mbcnt_lo_u32_b32 v0, -1, 0
	v_mbcnt_hi_u32_b32 v0, -1, v0
	s_mov_b32 s0, 0x100000
	v_add_u32_e32 v6, s1, v0
	v_cmp_gt_i32_e32 vcc, s0, v6
	s_cmp_lg_u32 s100, 0
	s_cbranch_scc1 .Lgl_go
	v_readlane_b32 s0, v231, 0
	s_nop 3
	s_bitcmp1_b32 s0, 0
	s_cbranch_scc0 .Lgl_go
	s_mov_b32 s100, 1
	s_mov_b64 s[2:3], exec
	s_branch .LBB0_631
.Lgl_go:
	s_and_saveexec_b64 s[2:3], vcc
	s_cbranch_execz .LBB0_631
	v_and_b32_e32 v4, 63, v0
	v_lshrrev_b32_e32 v0, 1, v0
	v_and_b32_e32 v2, 28, v0
	v_mov_b32_e32 v3, 0
	s_waitcnt lgkmcnt(0)
	v_lshl_add_u64 v[0:1], s[4:5], 0, v[2:3]
	s_mov_b64 s[6:7], 0x1ea00000
	v_lshlrev_b32_e32 v2, 4, v4
	v_lshl_add_u64 v[0:1], v[0:1], 0, s[6:7]
	v_lshl_add_u64 v[2:3], s[4:5], 0, v[2:3]
	s_mov_b64 s[6:7], 0x1ba00000
	s_lshl_b32 s0, s48, 9
	v_lshl_add_u64 v[4:5], v[2:3], 0, s[6:7]
	s_mov_b64 s[6:7], 0
	s_mov_b64 s[8:9], 0x4000
	s_mov_b64 s[10:11], 0x8000
	s_mov_b32 s1, 0xfffff

; __device__ __forceinline__ int lane_now() { int l; asm volatile("v_mbcnt_lo_u32_b32 %0, -1, 0\n\tv_mbcnt_hi_u32_b32 %0, -1, %0" : "=v"(l)); return l; }
; __host__ __device__ __forceinline__ int tpinv(int ac) { return (ac & ~255) + 128 * ((ac >> 5) & 1) + 32 * ((ac >> 6) & 3) + (ac & 31); }
; #define LF_LOADA(rt_) do { const bf16* ap_ = la + (size_t)((rt_) * 32 + i16) * KL2 + koff + 8 * kq; \
;         _Pragma("unroll") for (int ks_ = 0; ks_ < NKS; ++ks_) { afr[0][ks_] = *(const bf16x8*)(ap_ + 32 * ks_); afr[1][ks_] = *(const bf16x8*)(ap_ + 16 * KL2 + 32 * ks_); } } while (0)
; template <bool GATE> __device__ __forceinline__ void lora_fast(Ctx& C) {
;     constexpr int NKS = GATE ? 5 : 2, NG = GATE ? 2 : 4, NNB = 2 * NG, NCT = GATE ? 16 : 32;
;     const int lane = lane_now(), i16 = lane & 15, kq = lane >> 4;
;     const bf16* la = (const bf16*)(C.ws + WS_LORAA) + (GATE ? (size_t)S * KL2 : 0); const bf16* wt = (const bf16*)(C.ws + WS_WLORA);
;     const int ctask = C.gw % NCT, rg = C.gw / NCT, nrg = C.ngw / NCT;
;     if (rg >= nrg) return;
;     const int mode = GATE ? 2 : (ctask >> 4), cb = GATE ? ctask : (ctask & 15), koff = GATE ? 0 : 64 * mode;
;     const int ac0 = cb * (GATE ? 64 : 128);
;     bf16x8 bfr[NNB][NKS];
; #pragma unroll
;     for (int nb = 0; nb < NNB; ++nb) { const int ac = ac0 + 32 * (nb >> 1) + 8 * (i16 >> 2) + 4 * (nb & 1) + (i16 & 3); const int jrow = (GATE ? 4096 : 2048 * mode) + tpinv(ac);
; #pragma unroll
;         for (int ks = 0; ks < NKS; ++ks) bfr[nb][ks] = *(const bf16x8*)(wt + (size_t)jrow * KL2 + koff + 32 * ks + 8 * kq); }
;     const int z = GATE ? 0 : (ac0 >> 10), c0 = (ac0 & 1023) + 8 * kq;
;     f32x4 bias[NG][2];
; #pragma unroll
;     for (int g = 0; g < NG; ++g)
; #pragma unroll
;         for (int b = 0; b < 2; ++b) { bias[g][b] = (f32x4){0.f, 0.f, 0.f, 0.f}; if (!GATE) bias[g][b] = *(const f32x4*)((mode == 0 ? C.ka->in[8] : C.ka->in[10]) + z * RW + c0 + 32 * g + 4 * b); }
;     bf16* dst = GATE ? (bf16*)(C.ws + WS_GATE) : (bf16*)(C.ws + (mode == 0 ? WS_LW : WS_A)) + (size_t)z * S * RW;
;     const int ntile = S / 32;
;     bf16x8 afr[2][NKS];
;     ...
;     int rt = rg; if (rt >= ntile) return;
;     LF_LOADA(rt);
.LBB0_631:
	s_or_b64 exec, exec, s[2:3]
	s_cmp_eq_u32 s100, 2
	s_cbranch_scc1 .LBB0_643
	v_readlane_b32 s0, v231, 0
	s_lshl_b32 s0, s0, 3
	s_add_i32 s0, s92, s0
	s_ashr_i32 s1, s0, 31
	s_lshr_b32 s2, s1, 27
	s_add_i32 s2, s0, s2
	s_ashr_i32 s8, s2, 5
	s_waitcnt lgkmcnt(0)
	s_ashr_i32 s2, s48, 31
	s_lshr_b32 s2, s2, 30
	s_add_i32 s2, s48, s2
	s_ashr_i32 s9, s2, 2
	s_cmp_ge_i32 s8, s9
	s_waitcnt vmcnt(0)
	s_barrier
	v_mbcnt_lo_u32_b32 v0, -1, 0
	v_mbcnt_hi_u32_b32 v0, -1, v0
	s_cbranch_scc1 .LBB0_637
	s_cmpk_gt_i32 s0, 0x3fff
	s_cbranch_scc1 .LBB0_637
	s_lshl_b32 s10, s8, 5
	s_sub_i32 s11, s0, s10
	s_ashr_i32 s3, s11, 4
	s_lshl_b32 s2, s3, 6
	v_and_b32_e32 v182, 15, v0
	s_lshl_b32 s16, s11, 7
	v_lshlrev_b32_e32 v1, 1, v0
	v_and_b32_e32 v2, 3, v0
	s_lshl_b32 s13, s3, 11
	s_ashr_i32 s3, s2, 31
	v_ashrrev_i32_e32 v0, 1, v0
	s_and_b32 s12, s16, 0x780
	s_lshl_b64 s[6:7], s[2:3], 1
	v_and_b32_e32 v64, -8, v0
	s_add_u32 s2, s4, s6
	v_ashrrev_i32_e32 v65, 31, v64
	s_addc_u32 s3, s5, s7
	v_lshlrev_b64 v[112:113], 1, v[64:65]
	v_and_or_b32 v42, v1, 24, v2
	v_lshl_add_u64 v[0:1], s[2:3], 0, v[112:113]
	s_mov_b64 s[2:3], 0x3000000
	v_lshl_add_u64 v[56:57], v[0:1], 0, s[2:3]
	s_lshl_b32 s2, s11, 6
	s_and_b32 s2, s2, 64
	s_and_b32 s3, s16, 0x700
	s_or_b32 s2, s2, s3
	v_or_b32_e32 v34, s2, v42
	v_or_b32_e32 v0, s13, v34
	v_ashrrev_i32_e32 v1, 31, v0
	v_lshlrev_b64 v[0:1], 9, v[0:1]
	v_lshl_add_u64 v[8:9], v[56:57], 0, v[0:1]
	v_or_b32_e32 v26, 4, v34
	global_load_dwordx4 v[0:3], v[8:9], off
	global_load_dwordx4 v[4:7], v[8:9], off offset:64
	v_or_b32_e32 v8, s13, v26
	v_ashrrev_i32_e32 v9, 31, v8
	v_lshlrev_b64 v[8:9], 9, v[8:9]
	v_lshl_add_u64 v[16:17], v[56:57], 0, v[8:9]
	s_or_b32 s2, s13, 0x80
	global_load_dwordx4 v[8:11], v[16:17], off
	global_load_dwordx4 v[12:15], v[16:17], off offset:64
	v_or_b32_e32 v16, s2, v34
	v_ashrrev_i32_e32 v17, 31, v16
	v_lshlrev_b64 v[16:17], 9, v[16:17]
	v_lshl_add_u64 v[24:25], v[56:57], 0, v[16:17]
	global_load_dwordx4 v[16:19], v[24:25], off
	global_load_dwordx4 v[20:23], v[24:25], off offset:64
	v_or_b32_e32 v24, s2, v26
	v_ashrrev_i32_e32 v25, 31, v24
	v_lshlrev_b64 v[24:25], 9, v[24:25]
	v_lshl_add_u64 v[32:33], v[56:57], 0, v[24:25]
	v_or_b32_e32 v50, 32, v34
	global_load_dwordx4 v[24:27], v[32:33], off
	global_load_dwordx4 v[28:31], v[32:33], off offset:64
	v_or_b32_e32 v32, s13, v50
	v_ashrrev_i32_e32 v33, 31, v32
	v_lshlrev_b64 v[32:33], 9, v[32:33]
	v_lshl_add_u64 v[40:41], v[56:57], 0, v[32:33]
	v_or_b32_e32 v60, s12, v42
	global_load_dwordx4 v[32:35], v[40:41], off
	global_load_dwordx4 v[36:39], v[40:41], off offset:64
	v_or_b32_e32 v40, 0x44, v60
	v_lshrrev_b32_e32 v40, 1, v40
	s_movk_i32 s3, 0x71f
	v_mov_b32_e32 v41, 0x44
	v_and_b32_e32 v40, 0x60, v40
	v_bitop3_b32 v41, v60, s3, v41 bitop3:0xc8
	v_or3_b32 v40, v41, v40, s13
	v_ashrrev_i32_e32 v41, 31, v40
	v_lshlrev_b64 v[40:41], 9, v[40:41]
	v_lshl_add_u64 v[48:49], v[56:57], 0, v[40:41]
	global_load_dwordx4 v[40:43], v[48:49], off
	global_load_dwordx4 v[44:47], v[48:49], off offset:64
	v_or_b32_e32 v48, s2, v50
	v_ashrrev_i32_e32 v49, 31, v48
	v_lshlrev_b64 v[48:49], 9, v[48:49]
	v_lshl_add_u64 v[58:59], v[56:57], 0, v[48:49]
	global_load_dwordx4 v[48:51], v[58:59], off
	global_load_dwordx4 v[52:55], v[58:59], off offset:64
	v_or_b32_e32 v58, 0x64, v60
	v_lshrrev_b32_e32 v58, 1, v58
	v_mov_b32_e32 v59, 0x64
	v_and_b32_e32 v58, 0x60, v58
	v_bitop3_b32 v59, v60, s3, v59 bitop3:0xc8
	s_cmp_lt_u32 s11, 16
	v_or3_b32 v58, v59, v58, s2
	s_cselect_b64 s[2:3], -1, 0
	s_add_u32 s12, s4, 0x1000000
	s_addc_u32 s13, s5, 0
	s_and_b64 s[14:15], s[2:3], exec
	s_cselect_b32 s14, 64, 0x50
	s_add_u32 s14, s88, s14
	s_addc_u32 s15, s89, 0
	s_load_dwordx2 s[14:15], s[14:15], 0x0
	s_lshl_b32 s17, s11, 9
	s_and_b32 s17, s17, 0x1000
	v_ashrrev_i32_e32 v59, 31, v58
	v_lshlrev_b64 v[58:59], 9, v[58:59]
	s_waitcnt lgkmcnt(0)
	s_add_u32 s14, s14, s17
	s_addc_u32 s15, s15, 0
	s_and_b32 s16, s16, 0x380
	v_add_u32_e32 v114, s16, v64
	v_ashrrev_i32_e32 v115, 31, v114
	v_lshl_add_u64 v[66:67], v[56:57], 0, v[58:59]
	v_lshl_add_u64 v[96:97], v[114:115], 2, s[14:15]
	global_load_dwordx4 v[56:59], v[66:67], off
	global_load_dwordx4 v[60:63], v[66:67], off offset:64
	s_nop 0
	global_load_dwordx4 v[64:67], v[96:97], off offset:384
	global_load_dwordx4 v[68:71], v[96:97], off offset:400
	global_load_dwordx4 v[72:75], v[96:97], off offset:256
	global_load_dwordx4 v[76:79], v[96:97], off offset:272
	global_load_dwordx4 v[80:83], v[96:97], off offset:128
	global_load_dwordx4 v[84:87], v[96:97], off offset:144
	global_load_dwordx4 v[88:91], v[96:97], off
	global_load_dwordx4 v[92:95], v[96:97], off offset:16
	v_or_b32_e32 v96, s10, v182
	v_ashrrev_i32_e32 v97, 31, v96
	v_lshlrev_b64 v[96:97], 9, v[96:97]
	v_lshl_add_u64 v[96:97], s[12:13], 0, v[96:97]
	v_lshl_add_u64 v[96:97], v[96:97], 0, s[6:7]
	v_lshl_add_u64 v[116:117], v[96:97], 0, v[112:113]
	s_movk_i32 s14, 0x2000
	v_add_co_u32_e32 v118, vcc, s14, v116
	s_mov_b32 s16, 0x3a00000
	s_nop 0
	v_addc_co_u32_e32 v119, vcc, 0, v117, vcc
	global_load_dwordx4 v[96:99], v[116:117], off
	global_load_dwordx4 v[100:103], v[116:117], off offset:64
	global_load_dwordx4 v[104:107], v[118:119], off
	global_load_dwordx4 v[108:111], v[118:119], off offset:64
	s_and_b64 s[14:15], s[2:3], exec
	s_cselect_b32 s14, s16, 0x7a00000
	s_add_u32 s14, s4, s14
	s_addc_u32 s15, s5, 0
	s_lshl_b32 s11, s11, 22
	s_and_b32 s11, s11, 0x2000000
	s_add_u32 s14, s14, s11
	s_addc_u32 s15, s15, 0
	s_add_u32 s6, s12, s6
	s_addc_u32 s7, s13, s7
	v_lshl_add_u64 v[176:177], s[6:7], 0, v[112:113]
	s_add_i32 s6, s8, s9
	v_lshl_add_u64 v[178:179], v[114:115], 1, s[14:15]
	s_lshl_b32 s11, s6, 5
	s_lshl_b32 s12, s9, 5
	s_branch .LBB0_635

; #define LF_LOADA(rt_) do { const bf16* ap_ = la + (size_t)((rt_) * 32 + i16) * KL2 + koff + 8 * kq; \
;         _Pragma("unroll") for (int ks_ = 0; ks_ < NKS; ++ks_) { afr[0][ks_] = *(const bf16x8*)(ap_ + 32 * ks_); afr[1][ks_] = *(const bf16x8*)(ap_ + 16 * KL2 + 32 * ks_); } } while (0)
; #define PH(k, ...) do { if (ka->ph_lo <= (k) && (k) < ka->ph_hi) { MKCTX(); __VA_ARGS__; if ((k) == PROBE_DUP) { GSYNC(); __VA_ARGS__; } if ((k) + 1 < ka->ph_hi) GSYNC(); } } while (0)
; template <bool GATE> __device__ __forceinline__ void lora_fast(Ctx& C) {
;     ...
;     for (;;) {
;         f32x4 acc[2][NNB];
; #pragma unroll
;         for (int mb = 0; mb < 2; ++mb)
; #pragma unroll
;             for (int nb = 0; nb < NNB; ++nb) { acc[mb][nb] = (f32x4){0.f, 0.f, 0.f, 0.f};
; #pragma unroll
;                 for (int ks = 0; ks < NKS; ++ks) acc[mb][nb] = __builtin_amdgcn_mfma_f32_16x16x32_bf16(bfr[nb][ks], afr[mb][ks], acc[mb][nb], 0, 0, 0); }
;         const int t0 = rt * 32; const int nrt = rt + nrg; const bool more = nrt < ntile;
;         if (more) LF_LOADA(nrt);
; template <bool COOP>
; __global__ void __launch_bounds__(NTHR, 2) mega(Args args) {
;     ...
;     PH(P_GLORA, ph_attn_combine(C); __syncthreads(); ph_glora(C));
.LBB0_641:
	s_waitcnt vmcnt(9)
	v_mfma_f32_16x16x32_bf16 v[120:123], v[0:3], v[80:83], 0
	s_add_i32 s1, s1, s6
	s_cmpk_gt_i32 s1, 0x1ff
	s_cselect_b64 s[2:3], -1, 0
	s_waitcnt vmcnt(8)
	v_mfma_f32_16x16x32_bf16 v[120:123], v[4:7], v[84:87], v[120:123]
	s_and_b64 vcc, exec, s[2:3]
	s_waitcnt vmcnt(5)
	v_mfma_f32_16x16x32_bf16 v[120:123], v[8:11], v[96:99], v[120:123]
	s_waitcnt vmcnt(4)
	v_mfma_f32_16x16x32_bf16 v[120:123], v[12:15], v[100:103], v[120:123]
	s_waitcnt vmcnt(2)
	v_mfma_f32_16x16x32_bf16 v[144:147], v[16:19], v[108:111], v[120:123]
	v_mfma_f32_16x16x32_bf16 v[120:123], v[20:23], v[80:83], 0
	v_mfma_f32_16x16x32_bf16 v[120:123], v[24:27], v[84:87], v[120:123]
	v_mfma_f32_16x16x32_bf16 v[120:123], v[28:31], v[96:99], v[120:123]
	v_mfma_f32_16x16x32_bf16 v[120:123], v[32:35], v[100:103], v[120:123]
	v_mfma_f32_16x16x32_bf16 v[148:151], v[36:39], v[108:111], v[120:123]
	v_mfma_f32_16x16x32_bf16 v[120:123], v[40:43], v[80:83], 0
	v_mfma_f32_16x16x32_bf16 v[120:123], v[44:47], v[84:87], v[120:123]
	v_mfma_f32_16x16x32_bf16 v[120:123], v[48:51], v[96:99], v[120:123]
	v_mfma_f32_16x16x32_bf16 v[120:123], v[52:55], v[100:103], v[120:123]
	v_mfma_f32_16x16x32_bf16 v[136:139], v[56:59], v[108:111], v[120:123]
	v_mfma_f32_16x16x32_bf16 v[120:123], v[60:63], v[80:83], 0
	v_mfma_f32_16x16x32_bf16 v[120:123], v[64:67], v[84:87], v[120:123]
	v_mfma_f32_16x16x32_bf16 v[120:123], v[68:71], v[96:99], v[120:123]
	v_mfma_f32_16x16x32_bf16 v[120:123], v[72:75], v[100:103], v[120:123]
	v_mfma_f32_16x16x32_bf16 v[140:143], v[76:79], v[108:111], v[120:123]
	v_mfma_f32_16x16x32_bf16 v[120:123], v[0:3], v[104:107], 0
	v_mfma_f32_16x16x32_bf16 v[120:123], v[4:7], v[88:91], v[120:123]
	v_mfma_f32_16x16x32_bf16 v[120:123], v[8:11], v[92:95], v[120:123]
	s_waitcnt vmcnt(1)
	v_mfma_f32_16x16x32_bf16 v[120:123], v[12:15], v[112:115], v[120:123]
	s_waitcnt vmcnt(0)
	v_mfma_f32_16x16x32_bf16 v[124:127], v[16:19], v[116:119], v[120:123]
	v_mfma_f32_16x16x32_bf16 v[120:123], v[20:23], v[104:107], 0
	v_mfma_f32_16x16x32_bf16 v[120:123], v[24:27], v[88:91], v[120:123]
	v_mfma_f32_16x16x32_bf16 v[120:123], v[28:31], v[92:95], v[120:123]
	v_mfma_f32_16x16x32_bf16 v[120:123], v[32:35], v[112:115], v[120:123]
	v_mfma_f32_16x16x32_bf16 v[128:131], v[36:39], v[116:119], v[120:123]
	v_mfma_f32_16x16x32_bf16 v[120:123], v[40:43], v[104:107], 0
	v_mfma_f32_16x16x32_bf16 v[132:135], v[60:63], v[104:107], 0
	v_mfma_f32_16x16x32_bf16 v[120:123], v[44:47], v[88:91], v[120:123]
	v_mfma_f32_16x16x32_bf16 v[132:135], v[64:67], v[88:91], v[132:135]
	v_mfma_f32_16x16x32_bf16 v[120:123], v[48:51], v[92:95], v[120:123]
	v_mfma_f32_16x16x32_bf16 v[132:135], v[68:71], v[92:95], v[132:135]
	v_mfma_f32_16x16x32_bf16 v[120:123], v[52:55], v[112:115], v[120:123]
	v_mfma_f32_16x16x32_bf16 v[132:135], v[72:75], v[112:115], v[132:135]
	v_mfma_f32_16x16x32_bf16 v[120:123], v[56:59], v[116:119], v[120:123]
	v_mfma_f32_16x16x32_bf16 v[132:135], v[76:79], v[116:119], v[132:135]
	s_cbranch_vccnz .LBB0_640
	v_add_u32_e32 v80, s7, v156
	v_ashrrev_i32_e32 v81, 31, v80
	v_lshlrev_b64 v[80:81], 9, v[80:81]
	v_lshl_add_u64 v[108:109], v[152:153], 0, v[80:81]
	v_add_co_u32_e32 v116, vcc, 0x2000, v108
	s_nop 1
	v_addc_co_u32_e32 v117, vcc, 0, v109, vcc
	global_load_dwordx4 v[80:83], v[108:109], off
	global_load_dwordx4 v[84:87], v[108:109], off offset:64
	global_load_dwordx4 v[88:91], v[116:117], off offset:64
	global_load_dwordx4 v[92:95], v[116:117], off offset:128
	global_load_dwordx4 v[96:99], v[108:109], off offset:128
	global_load_dwordx4 v[100:103], v[108:109], off offset:192
	global_load_dwordx4 v[104:107], v[116:117], off
	s_nop 0
	global_load_dwordx4 v[108:111], v[108:109], off offset:256
	s_nop 0
	global_load_dwordx4 v[112:115], v[116:117], off offset:192
	s_nop 0
	global_load_dwordx4 v[116:119], v[116:117], off offset:256
	s_branch .LBB0_640
.LBB0_643:
	s_cmp_eq_u32 s100, 1
	s_cbranch_scc0 .Lgl_fin
	s_mov_b32 s100, 2
	s_branch .Lgl_setup
.Lgl_fin:
	s_load_dword s0, s[88:89], 0xdc
	s_waitcnt lgkmcnt(0)
	s_cmp_lt_i32 s0, 6
	s_cbranch_scc1 .LBB0_699
	s_getreg_b32 s0, hwreg(HW_REG_XCC_ID, 0, 4)
	s_cmp_lg_u32 s92, 0
	s_mov_b64 s[6:7], 0
	s_cbranch_scc1 .LBB0_646
	v_mbcnt_lo_u32_b32 v0, -1, 0
	v_mbcnt_hi_u32_b32 v0, -1, v0
	s_nop 0
	v_cmp_eq_u32_e32 vcc, 0, v0
	s_and_b64 s[6:7], vcc, exec
